# P15 carry-prefix loop software pipelined (two register sets, next 4 steps loaded before current 4 consumed)
# speedup vs baseline: 1.0078x; 1.0078x over previous
; __global__ void __launch_bounds__(512, 2) fwd_kernel(Params p) {
;     ...
; #pragma unroll 4
;                 for (int j = 0; j < ch; ++j) { const size_t ci = ((size_t)b * NCHUNK + j) * LRU_W + c; const f32x4 cp = *(const f32x4*)(carryP + ci), chh = *(const f32x4*)(carryH + ci);
;                     h[0] = cp.x * h[0] + chh.x; h[1] = cp.y * h[1] + chh.y; h[2] = cp.z * h[2] + chh.z; h[3] = cp.w * h[3] + chh.w; }
.LBB0_1504:
	v_add_co_u32_e32 v232, vcc, 0xffe7c000, v74
	s_nop 1
	v_addc_co_u32_e32 v233, vcc, -1, v75, vcc
	v_add_co_u32_e32 v234, vcc, 0xffffc000, v74
	s_nop 1
	v_addc_co_u32_e32 v235, vcc, -1, v75, vcc
	global_load_dwordx4 v[80:83], v[232:233], off offset:-2048
	global_load_dwordx4 v[84:87], v[234:235], off offset:-2048
	v_add_co_u32_e32 v232, vcc, 0xffe7d000, v74
	s_nop 1
	v_addc_co_u32_e32 v233, vcc, -1, v75, vcc
	v_add_co_u32_e32 v234, vcc, 0xffffd000, v74
	s_nop 1
	v_addc_co_u32_e32 v235, vcc, -1, v75, vcc
	global_load_dwordx4 v[88:91], v[232:233], off
	global_load_dwordx4 v[92:95], v[234:235], off
	v_add_co_u32_e32 v232, vcc, 0xffe7f000, v74
	s_nop 1
	v_addc_co_u32_e32 v233, vcc, -1, v75, vcc
	v_add_co_u32_e32 v234, vcc, 0xfffff000, v74
	s_nop 1
	v_addc_co_u32_e32 v235, vcc, -1, v75, vcc
	global_load_dwordx4 v[96:99], v[232:233], off offset:-2048
	global_load_dwordx4 v[100:103], v[234:235], off offset:-2048
	v_add_co_u32_e32 v232, vcc, 0xffe80000, v74
	s_nop 1
	v_addc_co_u32_e32 v233, vcc, -1, v75, vcc
	global_load_dwordx4 v[104:107], v[232:233], off
	global_load_dwordx4 v[108:111], v[74:75], off
	v_lshl_add_u64 v[74:75], v[74:75], 0, s[20:21]
	s_add_i32 s39, s39, 4
.Lp15_pipe:
	s_cmp_eq_u32 s38, s39
	s_cbranch_scc1 .Lp15_lastA
	v_add_co_u32_e32 v232, vcc, 0xffe7c000, v74
	s_nop 1
	v_addc_co_u32_e32 v233, vcc, -1, v75, vcc
	v_add_co_u32_e32 v234, vcc, 0xffffc000, v74
	s_nop 1
	v_addc_co_u32_e32 v235, vcc, -1, v75, vcc
	global_load_dwordx4 v[200:203], v[232:233], off offset:-2048
	global_load_dwordx4 v[204:207], v[234:235], off offset:-2048
	v_add_co_u32_e32 v232, vcc, 0xffe7d000, v74
	s_nop 1
	v_addc_co_u32_e32 v233, vcc, -1, v75, vcc
	v_add_co_u32_e32 v234, vcc, 0xffffd000, v74
	s_nop 1
	v_addc_co_u32_e32 v235, vcc, -1, v75, vcc
	global_load_dwordx4 v[208:211], v[232:233], off
	global_load_dwordx4 v[212:215], v[234:235], off
	v_add_co_u32_e32 v232, vcc, 0xffe7f000, v74
	s_nop 1
	v_addc_co_u32_e32 v233, vcc, -1, v75, vcc
	v_add_co_u32_e32 v234, vcc, 0xfffff000, v74
	s_nop 1
	v_addc_co_u32_e32 v235, vcc, -1, v75, vcc
	global_load_dwordx4 v[216:219], v[232:233], off offset:-2048
	global_load_dwordx4 v[220:223], v[234:235], off offset:-2048
	v_add_co_u32_e32 v232, vcc, 0xffe80000, v74
	s_nop 1
	v_addc_co_u32_e32 v233, vcc, -1, v75, vcc
	global_load_dwordx4 v[224:227], v[232:233], off
	global_load_dwordx4 v[228:231], v[74:75], off
	v_lshl_add_u64 v[74:75], v[74:75], 0, s[20:21]
	s_add_i32 s39, s39, 4
	s_waitcnt vmcnt(14)
	v_pk_fma_f32 v[72:73], v[72:73], v[80:81], v[84:85]
	v_pk_fma_f32 v[78:79], v[78:79], v[82:83], v[86:87]
	s_waitcnt vmcnt(12)
	v_pk_fma_f32 v[72:73], v[72:73], v[88:89], v[92:93]
	v_pk_fma_f32 v[78:79], v[78:79], v[90:91], v[94:95]
	s_waitcnt vmcnt(10)
	v_pk_fma_f32 v[72:73], v[72:73], v[96:97], v[100:101]
	v_pk_fma_f32 v[78:79], v[78:79], v[98:99], v[102:103]
	s_waitcnt vmcnt(8)
	v_pk_fma_f32 v[72:73], v[72:73], v[104:105], v[108:109]
	v_pk_fma_f32 v[78:79], v[78:79], v[106:107], v[110:111]
	s_cmp_eq_u32 s38, s39
	s_cbranch_scc1 .Lp15_lastB
	v_add_co_u32_e32 v232, vcc, 0xffe7c000, v74
	s_nop 1
	v_addc_co_u32_e32 v233, vcc, -1, v75, vcc
	v_add_co_u32_e32 v234, vcc, 0xffffc000, v74
	s_nop 1
	v_addc_co_u32_e32 v235, vcc, -1, v75, vcc
	global_load_dwordx4 v[80:83], v[232:233], off offset:-2048
	global_load_dwordx4 v[84:87], v[234:235], off offset:-2048
	v_add_co_u32_e32 v232, vcc, 0xffe7d000, v74
	s_nop 1
	v_addc_co_u32_e32 v233, vcc, -1, v75, vcc
	v_add_co_u32_e32 v234, vcc, 0xffffd000, v74
	s_nop 1
	v_addc_co_u32_e32 v235, vcc, -1, v75, vcc
	global_load_dwordx4 v[88:91], v[232:233], off
	global_load_dwordx4 v[92:95], v[234:235], off
	v_add_co_u32_e32 v232, vcc, 0xffe7f000, v74
	s_nop 1
	v_addc_co_u32_e32 v233, vcc, -1, v75, vcc
	v_add_co_u32_e32 v234, vcc, 0xfffff000, v74
	s_nop 1
	v_addc_co_u32_e32 v235, vcc, -1, v75, vcc
	global_load_dwordx4 v[96:99], v[232:233], off offset:-2048
	global_load_dwordx4 v[100:103], v[234:235], off offset:-2048
	v_add_co_u32_e32 v232, vcc, 0xffe80000, v74
	s_nop 1
	v_addc_co_u32_e32 v233, vcc, -1, v75, vcc
	global_load_dwordx4 v[104:107], v[232:233], off
	global_load_dwordx4 v[108:111], v[74:75], off
	v_lshl_add_u64 v[74:75], v[74:75], 0, s[20:21]
	s_add_i32 s39, s39, 4
	s_waitcnt vmcnt(14)
	v_pk_fma_f32 v[72:73], v[72:73], v[200:201], v[204:205]
	v_pk_fma_f32 v[78:79], v[78:79], v[202:203], v[206:207]
	s_waitcnt vmcnt(12)
	v_pk_fma_f32 v[72:73], v[72:73], v[208:209], v[212:213]
	v_pk_fma_f32 v[78:79], v[78:79], v[210:211], v[214:215]
	s_waitcnt vmcnt(10)
	v_pk_fma_f32 v[72:73], v[72:73], v[216:217], v[220:221]
	v_pk_fma_f32 v[78:79], v[78:79], v[218:219], v[222:223]
	s_waitcnt vmcnt(8)
	v_pk_fma_f32 v[72:73], v[72:73], v[224:225], v[228:229]
	v_pk_fma_f32 v[78:79], v[78:79], v[226:227], v[230:231]
	s_branch .Lp15_pipe
.Lp15_lastA:
	s_waitcnt vmcnt(6)
	v_pk_fma_f32 v[72:73], v[72:73], v[80:81], v[84:85]
	v_pk_fma_f32 v[78:79], v[78:79], v[82:83], v[86:87]
	s_waitcnt vmcnt(4)
	v_pk_fma_f32 v[72:73], v[72:73], v[88:89], v[92:93]
	v_pk_fma_f32 v[78:79], v[78:79], v[90:91], v[94:95]
	s_waitcnt vmcnt(2)
	v_pk_fma_f32 v[72:73], v[72:73], v[96:97], v[100:101]
	v_pk_fma_f32 v[78:79], v[78:79], v[98:99], v[102:103]
	s_waitcnt vmcnt(0)
	v_pk_fma_f32 v[72:73], v[72:73], v[104:105], v[108:109]
	v_pk_fma_f32 v[78:79], v[78:79], v[106:107], v[110:111]
	s_branch .Lp15_done
.Lp15_lastB:
	s_waitcnt vmcnt(6)
	v_pk_fma_f32 v[72:73], v[72:73], v[200:201], v[204:205]
	v_pk_fma_f32 v[78:79], v[78:79], v[202:203], v[206:207]
	s_waitcnt vmcnt(4)
	v_pk_fma_f32 v[72:73], v[72:73], v[208:209], v[212:213]
	v_pk_fma_f32 v[78:79], v[78:79], v[210:211], v[214:215]
	s_waitcnt vmcnt(2)
	v_pk_fma_f32 v[72:73], v[72:73], v[216:217], v[220:221]
	v_pk_fma_f32 v[78:79], v[78:79], v[218:219], v[222:223]
	s_waitcnt vmcnt(0)
	v_pk_fma_f32 v[72:73], v[72:73], v[224:225], v[228:229]
	v_pk_fma_f32 v[78:79], v[78:79], v[226:227], v[230:231]
.Lp15_done:
	s_and_b32 s39, s46, 3
	s_cmp_eq_u32 s39, 0
	s_cbranch_scc0 .LBB0_1508
	s_branch .LBB0_1510
